# v25 + in-projection K-loop: per phase the 32 MFMAs are issued k-step by k-step with the four MFMAs sharing one src1 fragment back-to-back (bit-identical)
# baseline (speedup 1.0000x reference)
; #define PG8_STAGE(bufoff, gbase, voff) do { _Pragma("unroll") for (int _i = 0; _i < 2; ++_i) \
;         __builtin_amdgcn_global_load_lds((const unsigned*)((const char*)(gbase) + (voff)[_i]), (PG8_LAS unsigned*)(lds + (bufoff) + ldsw + _i * 8192), 16, 0, 0); } while (0)
; #define PG8_LDA(dst, b, h) do { _Pragma("unroll") for (int m = 0; m < 4; ++m) _Pragma("unroll") for (int k = 0; k < 2; ++k) dst[m][k] = *(const PG8_LAS bf16x8*)(lds + PG8_SA(b, h) + aoff + m * 2048 + k * 1024); } while (0)
; #define PG8_LDB(dst, b, h) do { _Pragma("unroll") for (int n = 0; n < 2; ++n) _Pragma("unroll") for (int k = 0; k < 2; ++k) dst[n][k] = *(const PG8_LAS bf16x8*)(lds + PG8_SB(b, h) + boff + n * 2048 + k * 1024); } while (0)
; #define PG8_MMA(ai, bj, At, Bt) do { __builtin_amdgcn_s_setprio(1); _Pragma("unroll") for (int m = 0; m < 4; ++m) _Pragma("unroll") for (int n = 0; n < 2; ++n) _Pragma("unroll") for (int k = 0; k < 2; ++k) \
;         acc[ai][bj][m][n] = __builtin_amdgcn_mfma_f32_16x16x32_bf16(Bt[n][k], At[m][k], acc[ai][bj][m][n], 0, 0, 0); __builtin_amdgcn_s_setprio(0); } while (0)
; #define PG8_WAIT_V(n) asm volatile("s_waitcnt vmcnt(" #n ")" ::: "memory")
; #define PG8_WAIT_L(n) asm volatile("s_waitcnt lgkmcnt(" #n ")" ::: "memory")
; template <class Epi, class Sched, bool ALIGN_EPI = false, bool SP2 = false>
; __device__ __forceinline__ void gemm_phase(PG8_LAS unsigned char* lds, const Gemm g, const Sched& S, const Epi& E, const int tid) {
;     ...
;             const bool last = (t == nt - 2);
;             const char* a1 = cA + (size_t)(t + 1) * kstep;
;             const char* a2 = last ? nA : cA + (size_t)(t + 2) * kstep; const char* b2 = last ? nB : cB + (size_t)(t + 2) * kstep;
;             const char* a3 = a2 + kstep; const char* b3 = b2 + kstep;
;             if (last && has_next) S.a_ready(nxt);
;             if constexpr (SP2) {
;             PG8_LDB(B0, 0, 0); PG8_LDB(B1, 0, 1); PG8_SCHED; PG8_LDA(At, 0, 0); PG8_STAGE(PG8_SA(1, 1), a1 + hstepA, voffA);
;             PG8_WAIT_V(8); PG8_WAIT_L(0); PG8_BAR; PG8_MMA(0, 0, At, B0); PG8_MMA(0, 1, At, B1); PG8_BAR; PG8_SCHED;
;             PG8_LDA(At, 0, 1); PG8_STAGE(PG8_SB(0, 0), b2, voffB); PG8_STAGE(PG8_SB(0, 1), b2 + hstepB, voffB); PG8_STAGE(PG8_SA(0, 0), a2, voffA);
;             PG8_WAIT_V(8); PG8_WAIT_L(0); PG8_BAR; PG8_MMA(1, 0, At, B0); PG8_MMA(1, 1, At, B1); PG8_BAR; PG8_SCHED;
.LBB0_175:
	s_add_u32 s22, s6, 0xfff80080
	s_addc_u32 s23, s7, -1
	s_add_i32 s60, 0, 0x10000
	s_cmp_eq_u32 s59, 28
	s_cselect_b32 s25, s17, s23
	s_cselect_b32 s24, s27, s22
	s_cselect_b32 s23, s15, s43
	s_cselect_b32 s22, s28, s29
	s_add_i32 s62, 0, 0x14000
	v_add_u32_e32 v140, s60, v225
	v_add_u32_e32 v156, s62, v225
	ds_read_b128 v[128:131], v140
	ds_read_b128 v[132:135], v140 offset:1024
	ds_read_b128 v[136:139], v140 offset:2048
	ds_read_b128 v[140:143], v140 offset:3072
	ds_read_b128 v[144:147], v156
	ds_read_b128 v[148:151], v156 offset:1024
	ds_read_b128 v[152:155], v156 offset:2048
	ds_read_b128 v[156:159], v156 offset:3072
	v_lshl_add_u64 v[202:203], s[6:7], 0, v[186:187]
	s_add_i32 m0, s46, 0xc000
	ds_read_b128 v[160:163], v226
	ds_read_b128 v[164:167], v226 offset:1024
	ds_read_b128 v[168:171], v226 offset:2048
	ds_read_b128 v[172:175], v226 offset:3072
	ds_read_b128 v[188:191], v226 offset:4096
	ds_read_b128 v[194:197], v226 offset:5120
	ds_read_b128 v[198:201], v226 offset:6144
	ds_read_b128 v[218:221], v226 offset:7168
	global_load_lds_dwordx4 v[202:203], off
	v_lshl_add_u64 v[202:203], s[6:7], 0, v[184:185]
	s_add_i32 m0, s46, 0xe000
	s_nop 0
	global_load_lds_dwordx4 v[202:203], off
	s_waitcnt vmcnt(8)
	s_waitcnt lgkmcnt(0)
	s_barrier
	s_setprio 1
	s_waitcnt lgkmcnt(0)
	v_mfma_f32_16x16x32_bf16 v[120:123], v[128:131], v[160:163], v[120:123]
	v_mfma_f32_16x16x32_bf16 v[112:115], v[136:139], v[160:163], v[112:115]
	v_mfma_f32_16x16x32_bf16 v[124:127], v[144:147], v[160:163], v[124:127]
	v_mfma_f32_16x16x32_bf16 v[116:119], v[152:155], v[160:163], v[116:119]
	v_mfma_f32_16x16x32_bf16 v[76:79], v[128:131], v[168:171], v[76:79]
	v_mfma_f32_16x16x32_bf16 v[60:63], v[136:139], v[168:171], v[60:63]
	v_mfma_f32_16x16x32_bf16 v[84:87], v[144:147], v[168:171], v[84:87]
	v_mfma_f32_16x16x32_bf16 v[68:71], v[152:155], v[168:171], v[68:71]
	v_mfma_f32_16x16x32_bf16 v[52:55], v[128:131], v[188:191], v[52:55]
	v_mfma_f32_16x16x32_bf16 v[36:39], v[136:139], v[188:191], v[36:39]
	v_mfma_f32_16x16x32_bf16 v[64:67], v[144:147], v[188:191], v[64:67]
	v_mfma_f32_16x16x32_bf16 v[48:51], v[152:155], v[188:191], v[48:51]
	v_mfma_f32_16x16x32_bf16 v[32:35], v[128:131], v[198:201], v[32:35]
	v_mfma_f32_16x16x32_bf16 v[24:27], v[136:139], v[198:201], v[24:27]
	v_mfma_f32_16x16x32_bf16 v[44:47], v[144:147], v[198:201], v[44:47]
	v_mfma_f32_16x16x32_bf16 v[28:31], v[152:155], v[198:201], v[28:31]
	s_setprio 0
	s_setprio 1
	v_mfma_f32_16x16x32_bf16 v[120:123], v[132:135], v[164:167], v[120:123]
	v_mfma_f32_16x16x32_bf16 v[112:115], v[140:143], v[164:167], v[112:115]
	v_mfma_f32_16x16x32_bf16 v[124:127], v[148:151], v[164:167], v[124:127]
	v_mfma_f32_16x16x32_bf16 v[116:119], v[156:159], v[164:167], v[116:119]
	v_mfma_f32_16x16x32_bf16 v[76:79], v[132:135], v[172:175], v[76:79]
	v_mfma_f32_16x16x32_bf16 v[60:63], v[140:143], v[172:175], v[60:63]
	v_mfma_f32_16x16x32_bf16 v[84:87], v[148:151], v[172:175], v[84:87]
	v_mfma_f32_16x16x32_bf16 v[68:71], v[156:159], v[172:175], v[68:71]
	v_mfma_f32_16x16x32_bf16 v[52:55], v[132:135], v[194:197], v[52:55]
	v_mfma_f32_16x16x32_bf16 v[36:39], v[140:143], v[194:197], v[36:39]
	v_mfma_f32_16x16x32_bf16 v[64:67], v[148:151], v[194:197], v[64:67]
	v_mfma_f32_16x16x32_bf16 v[48:51], v[156:159], v[194:197], v[48:51]
	v_mfma_f32_16x16x32_bf16 v[32:35], v[132:135], v[218:221], v[32:35]
	v_mfma_f32_16x16x32_bf16 v[24:27], v[140:143], v[218:221], v[24:27]
	v_mfma_f32_16x16x32_bf16 v[44:47], v[148:151], v[218:221], v[44:47]
	v_mfma_f32_16x16x32_bf16 v[28:31], v[156:159], v[218:221], v[28:31]
	s_setprio 0
	s_barrier
	s_add_i32 s60, s60, s37
	v_lshl_add_u64 v[202:203], s[22:23], 0, v[180:181]
	s_mov_b32 m0, s60
	ds_read_b128 v[160:163], v226 offset:16384
	ds_read_b128 v[164:167], v226 offset:17408
	ds_read_b128 v[168:171], v226 offset:18432
	ds_read_b128 v[172:175], v226 offset:19456
	ds_read_b128 v[188:191], v226 offset:20480
	ds_read_b128 v[194:197], v226 offset:21504
	ds_read_b128 v[198:201], v226 offset:22528
	ds_read_b128 v[218:221], v226 offset:23552
	global_load_lds_dwordx4 v[202:203], off
	s_add_i32 m0, s60, 0x2000
	s_add_u32 s60, s22, 0x80000
	v_lshl_add_u64 v[206:207], s[22:23], 0, v[176:177]
	s_addc_u32 s61, s23, 0
	s_add_i32 s62, s62, s37
	global_load_lds_dwordx4 v[206:207], off
	v_lshl_add_u64 v[208:209], s[60:61], 0, v[180:181]
	s_mov_b32 m0, s62
	v_lshl_add_u64 v[214:215], s[24:25], 0, v[178:179]
	global_load_lds_dwordx4 v[208:209], off
	v_lshl_add_u64 v[208:209], s[60:61], 0, v[176:177]
	s_add_i32 m0, s62, 0x2000
	s_nop 0
	global_load_lds_dwordx4 v[208:209], off
	v_lshl_add_u64 v[208:209], s[24:25], 0, v[182:183]
	s_mov_b32 m0, s46
	s_nop 0
	global_load_lds_dwordx4 v[208:209], off
	s_mov_b32 m0, s47
	s_nop 0
	global_load_lds_dwordx4 v[214:215], off
	s_waitcnt vmcnt(8)
	s_waitcnt lgkmcnt(0)
	s_barrier
; #define PG8_STAGE(bufoff, gbase, voff) do { _Pragma("unroll") for (int _i = 0; _i < 2; ++_i) \
;         __builtin_amdgcn_global_load_lds((const unsigned*)((const char*)(gbase) + (voff)[_i]), (PG8_LAS unsigned*)(lds + (bufoff) + ldsw + _i * 8192), 16, 0, 0); } while (0)
; #define PG8_LDA(dst, b, h) do { _Pragma("unroll") for (int m = 0; m < 4; ++m) _Pragma("unroll") for (int k = 0; k < 2; ++k) dst[m][k] = *(const PG8_LAS bf16x8*)(lds + PG8_SA(b, h) + aoff + m * 2048 + k * 1024); } while (0)
; #define PG8_LDB(dst, b, h) do { _Pragma("unroll") for (int n = 0; n < 2; ++n) _Pragma("unroll") for (int k = 0; k < 2; ++k) dst[n][k] = *(const PG8_LAS bf16x8*)(lds + PG8_SB(b, h) + boff + n * 2048 + k * 1024); } while (0)
; #define PG8_MMA(ai, bj, At, Bt) do { __builtin_amdgcn_s_setprio(1); _Pragma("unroll") for (int m = 0; m < 4; ++m) _Pragma("unroll") for (int n = 0; n < 2; ++n) _Pragma("unroll") for (int k = 0; k < 2; ++k) \
;         acc[ai][bj][m][n] = __builtin_amdgcn_mfma_f32_16x16x32_bf16(Bt[n][k], At[m][k], acc[ai][bj][m][n], 0, 0, 0); __builtin_amdgcn_s_setprio(0); } while (0)
; #define PG8_WAIT_V(n) asm volatile("s_waitcnt vmcnt(" #n ")" ::: "memory")
; #define PG8_WAIT_L(n) asm volatile("s_waitcnt lgkmcnt(" #n ")" ::: "memory")
; #define PG8_BAR __builtin_amdgcn_s_barrier()
; #define PG8_SCHED __builtin_amdgcn_sched_barrier(0)
; template <class Epi, class Sched, bool ALIGN_EPI = false, bool SP2 = false>
; __device__ __forceinline__ void gemm_phase(PG8_LAS unsigned char* lds, const Gemm g, const Sched& S, const Epi& E, const int tid) {
;     ...
;             PG8_WAIT_V(8); PG8_WAIT_L(0); PG8_BAR; PG8_MMA(1, 0, At, B0); PG8_MMA(1, 1, At, B1); PG8_BAR; PG8_SCHED;
;             PG8_LDB(B0, 1, 0); PG8_LDB(B1, 1, 1); PG8_SCHED; PG8_LDA(At, 1, 0); PG8_STAGE(PG8_SA(0, 1), a2 + hstepA, voffA);
;             PG8_WAIT_V(8); PG8_WAIT_L(0); PG8_BAR; PG8_MMA(0, 0, At, B0); PG8_MMA(0, 1, At, B1); PG8_BAR; PG8_SCHED;
	s_setprio 1
	s_waitcnt lgkmcnt(0)
	v_mfma_f32_16x16x32_bf16 v[96:99], v[128:131], v[160:163], v[96:99]
	v_mfma_f32_16x16x32_bf16 v[100:103], v[136:139], v[160:163], v[100:103]
	v_mfma_f32_16x16x32_bf16 v[108:111], v[144:147], v[160:163], v[108:111]
	v_mfma_f32_16x16x32_bf16 v[104:107], v[152:155], v[160:163], v[104:107]
	v_mfma_f32_16x16x32_bf16 v[72:75], v[128:131], v[168:171], v[72:75]
	v_mfma_f32_16x16x32_bf16 v[80:83], v[136:139], v[168:171], v[80:83]
	v_mfma_f32_16x16x32_bf16 v[92:95], v[144:147], v[168:171], v[92:95]
	v_mfma_f32_16x16x32_bf16 v[88:91], v[152:155], v[168:171], v[88:91]
	v_mfma_f32_16x16x32_bf16 v[16:19], v[128:131], v[188:191], v[16:19]
	v_mfma_f32_16x16x32_bf16 v[20:23], v[136:139], v[188:191], v[20:23]
	v_mfma_f32_16x16x32_bf16 v[56:59], v[144:147], v[188:191], v[56:59]
	v_mfma_f32_16x16x32_bf16 v[40:43], v[152:155], v[188:191], v[40:43]
	v_mfma_f32_16x16x32_bf16 v[0:3], v[128:131], v[198:201], v[0:3]
	v_mfma_f32_16x16x32_bf16 v[4:7], v[136:139], v[198:201], v[4:7]
	v_mfma_f32_16x16x32_bf16 v[8:11], v[144:147], v[198:201], v[8:11]
	v_mfma_f32_16x16x32_bf16 v[12:15], v[152:155], v[198:201], v[12:15]
	s_setprio 0
	s_setprio 1
	v_mfma_f32_16x16x32_bf16 v[96:99], v[132:135], v[164:167], v[96:99]
	v_mfma_f32_16x16x32_bf16 v[100:103], v[140:143], v[164:167], v[100:103]
	v_mfma_f32_16x16x32_bf16 v[108:111], v[148:151], v[164:167], v[108:111]
	v_mfma_f32_16x16x32_bf16 v[104:107], v[156:159], v[164:167], v[104:107]
	v_mfma_f32_16x16x32_bf16 v[72:75], v[132:135], v[172:175], v[72:75]
	v_mfma_f32_16x16x32_bf16 v[80:83], v[140:143], v[172:175], v[80:83]
	v_mfma_f32_16x16x32_bf16 v[92:95], v[148:151], v[172:175], v[92:95]
	v_mfma_f32_16x16x32_bf16 v[88:91], v[156:159], v[172:175], v[88:91]
	v_mfma_f32_16x16x32_bf16 v[16:19], v[132:135], v[194:197], v[16:19]
	v_mfma_f32_16x16x32_bf16 v[20:23], v[140:143], v[194:197], v[20:23]
	v_mfma_f32_16x16x32_bf16 v[56:59], v[148:151], v[194:197], v[56:59]
	v_mfma_f32_16x16x32_bf16 v[40:43], v[156:159], v[194:197], v[40:43]
	v_mfma_f32_16x16x32_bf16 v[0:3], v[132:135], v[218:221], v[0:3]
	v_mfma_f32_16x16x32_bf16 v[4:7], v[140:143], v[218:221], v[4:7]
	v_mfma_f32_16x16x32_bf16 v[8:11], v[148:151], v[218:221], v[8:11]
	v_mfma_f32_16x16x32_bf16 v[12:15], v[156:159], v[218:221], v[12:15]
	s_setprio 0
	s_barrier
	s_add_i32 s60, 0, 0x18000
	s_add_i32 s61, 0, 0x1c000
	v_add_u32_e32 v140, s60, v225
	v_add_u32_e32 v156, s61, v225
	ds_read_b128 v[128:131], v140
	ds_read_b128 v[132:135], v140 offset:1024
	ds_read_b128 v[136:139], v140 offset:2048
	ds_read_b128 v[140:143], v140 offset:3072
	ds_read_b128 v[144:147], v156
	ds_read_b128 v[148:151], v156 offset:1024
	ds_read_b128 v[152:155], v156 offset:2048
	ds_read_b128 v[156:159], v156 offset:3072
	s_add_u32 s24, s24, 0x80000
	s_addc_u32 s25, s25, 0
	s_mov_b32 m0, s48
	v_lshl_add_u64 v[216:217], s[24:25], 0, v[182:183]
	ds_read_b128 v[160:163], v226 offset:32768
	ds_read_b128 v[164:167], v226 offset:33792
	ds_read_b128 v[168:171], v226 offset:34816
	ds_read_b128 v[172:175], v226 offset:35840
	ds_read_b128 v[188:191], v226 offset:36864
	ds_read_b128 v[194:197], v226 offset:37888
	ds_read_b128 v[198:201], v226 offset:38912
	ds_read_b128 v[218:221], v226 offset:39936
	global_load_lds_dwordx4 v[216:217], off
	v_lshl_add_u64 v[216:217], s[24:25], 0, v[178:179]
	s_mov_b32 m0, s49
	s_nop 0
	global_load_lds_dwordx4 v[216:217], off
	s_waitcnt vmcnt(8)
	s_waitcnt lgkmcnt(0)
	s_barrier
	s_setprio 1
	s_waitcnt lgkmcnt(0)
	v_mfma_f32_16x16x32_bf16 v[120:123], v[128:131], v[160:163], v[120:123]
	v_mfma_f32_16x16x32_bf16 v[112:115], v[136:139], v[160:163], v[112:115]
	v_mfma_f32_16x16x32_bf16 v[124:127], v[144:147], v[160:163], v[124:127]
	v_mfma_f32_16x16x32_bf16 v[116:119], v[152:155], v[160:163], v[116:119]
	v_mfma_f32_16x16x32_bf16 v[76:79], v[128:131], v[168:171], v[76:79]
	v_mfma_f32_16x16x32_bf16 v[60:63], v[136:139], v[168:171], v[60:63]
	v_mfma_f32_16x16x32_bf16 v[84:87], v[144:147], v[168:171], v[84:87]
	v_mfma_f32_16x16x32_bf16 v[68:71], v[152:155], v[168:171], v[68:71]
	v_mfma_f32_16x16x32_bf16 v[52:55], v[128:131], v[188:191], v[52:55]
	v_mfma_f32_16x16x32_bf16 v[36:39], v[136:139], v[188:191], v[36:39]
	v_mfma_f32_16x16x32_bf16 v[64:67], v[144:147], v[188:191], v[64:67]
	v_mfma_f32_16x16x32_bf16 v[48:51], v[152:155], v[188:191], v[48:51]
	v_mfma_f32_16x16x32_bf16 v[32:35], v[128:131], v[198:201], v[32:35]
	v_mfma_f32_16x16x32_bf16 v[24:27], v[136:139], v[198:201], v[24:27]
	v_mfma_f32_16x16x32_bf16 v[44:47], v[144:147], v[198:201], v[44:47]
	v_mfma_f32_16x16x32_bf16 v[28:31], v[152:155], v[198:201], v[28:31]
	s_setprio 0
	s_setprio 1
	v_mfma_f32_16x16x32_bf16 v[120:123], v[132:135], v[164:167], v[120:123]
	v_mfma_f32_16x16x32_bf16 v[112:115], v[140:143], v[164:167], v[112:115]
	v_mfma_f32_16x16x32_bf16 v[124:127], v[148:151], v[164:167], v[124:127]
	v_mfma_f32_16x16x32_bf16 v[116:119], v[156:159], v[164:167], v[116:119]
	v_mfma_f32_16x16x32_bf16 v[76:79], v[132:135], v[172:175], v[76:79]
	v_mfma_f32_16x16x32_bf16 v[60:63], v[140:143], v[172:175], v[60:63]
	v_mfma_f32_16x16x32_bf16 v[84:87], v[148:151], v[172:175], v[84:87]
	v_mfma_f32_16x16x32_bf16 v[68:71], v[156:159], v[172:175], v[68:71]
	v_mfma_f32_16x16x32_bf16 v[52:55], v[132:135], v[194:197], v[52:55]
	v_mfma_f32_16x16x32_bf16 v[36:39], v[140:143], v[194:197], v[36:39]
	v_mfma_f32_16x16x32_bf16 v[64:67], v[148:151], v[194:197], v[64:67]
	v_mfma_f32_16x16x32_bf16 v[48:51], v[156:159], v[194:197], v[48:51]
	v_mfma_f32_16x16x32_bf16 v[32:35], v[132:135], v[218:221], v[32:35]
	v_mfma_f32_16x16x32_bf16 v[24:27], v[140:143], v[218:221], v[24:27]
	v_mfma_f32_16x16x32_bf16 v[44:47], v[148:151], v[218:221], v[44:47]
	v_mfma_f32_16x16x32_bf16 v[28:31], v[156:159], v[218:221], v[28:31]
	s_setprio 0
	s_barrier
; #define PG8_STAGE(bufoff, gbase, voff) do { _Pragma("unroll") for (int _i = 0; _i < 2; ++_i) \
;         __builtin_amdgcn_global_load_lds((const unsigned*)((const char*)(gbase) + (voff)[_i]), (PG8_LAS unsigned*)(lds + (bufoff) + ldsw + _i * 8192), 16, 0, 0); } while (0)
; #define PG8_LDA(dst, b, h) do { _Pragma("unroll") for (int m = 0; m < 4; ++m) _Pragma("unroll") for (int k = 0; k < 2; ++k) dst[m][k] = *(const PG8_LAS bf16x8*)(lds + PG8_SA(b, h) + aoff + m * 2048 + k * 1024); } while (0)
; #define PG8_MMA(ai, bj, At, Bt) do { __builtin_amdgcn_s_setprio(1); _Pragma("unroll") for (int m = 0; m < 4; ++m) _Pragma("unroll") for (int n = 0; n < 2; ++n) _Pragma("unroll") for (int k = 0; k < 2; ++k) \
;         acc[ai][bj][m][n] = __builtin_amdgcn_mfma_f32_16x16x32_bf16(Bt[n][k], At[m][k], acc[ai][bj][m][n], 0, 0, 0); __builtin_amdgcn_s_setprio(0); } while (0)
; #define PG8_WAIT_V(n) asm volatile("s_waitcnt vmcnt(" #n ")" ::: "memory")
; #define PG8_WAIT_L(n) asm volatile("s_waitcnt lgkmcnt(" #n ")" ::: "memory")
; #define PG8_BAR __builtin_amdgcn_s_barrier()
; #define PG8_SCHED __builtin_amdgcn_sched_barrier(0)
; template <class Epi, class Sched, bool ALIGN_EPI = false, bool SP2 = false>
; __device__ __forceinline__ void gemm_phase(PG8_LAS unsigned char* lds, const Gemm g, const Sched& S, const Epi& E, const int tid) {
;     ...
;             PG8_LDA(At, 1, 1); PG8_STAGE(PG8_SB(1, 0), b3, voffB); PG8_STAGE(PG8_SB(1, 1), b3 + hstepB, voffB); PG8_STAGE(PG8_SA(1, 0), a3, voffA);
;             PG8_WAIT_V(8); PG8_WAIT_L(0); PG8_BAR; PG8_MMA(1, 0, At, B0); PG8_MMA(1, 1, At, B1); PG8_BAR; PG8_SCHED;
	s_add_i32 s24, s60, s37
	v_lshl_add_u64 v[202:203], v[202:203], 0, s[82:83]
	s_mov_b32 m0, s24
	ds_read_b128 v[160:163], v226 offset:49152
	ds_read_b128 v[164:167], v226 offset:50176
	ds_read_b128 v[168:171], v226 offset:51200
	ds_read_b128 v[172:175], v226 offset:52224
	ds_read_b128 v[188:191], v226 offset:53248
	ds_read_b128 v[194:197], v226 offset:54272
	ds_read_b128 v[198:201], v226 offset:55296
	ds_read_b128 v[218:221], v226 offset:56320
	global_load_lds_dwordx4 v[202:203], off
	s_add_i32 m0, s24, 0x2000
	s_add_u32 s22, s22, 0x80080
	v_lshl_add_u64 v[202:203], v[206:207], 0, s[82:83]
	s_addc_u32 s23, s23, 0
	s_add_i32 s24, s61, s37
	global_load_lds_dwordx4 v[202:203], off
	v_lshl_add_u64 v[202:203], s[22:23], 0, v[180:181]
	s_mov_b32 m0, s24
	s_nop 0
	global_load_lds_dwordx4 v[202:203], off
	v_lshl_add_u64 v[202:203], s[22:23], 0, v[176:177]
	s_add_i32 m0, s24, 0x2000
	s_nop 0
	global_load_lds_dwordx4 v[202:203], off
	v_lshl_add_u64 v[202:203], v[208:209], 0, s[82:83]
	s_mov_b32 m0, s54
	s_nop 0
	global_load_lds_dwordx4 v[202:203], off
	v_lshl_add_u64 v[202:203], v[214:215], 0, s[82:83]
	s_mov_b32 m0, s55
	s_nop 0
	global_load_lds_dwordx4 v[202:203], off
	s_waitcnt vmcnt(8)
	s_waitcnt lgkmcnt(0)
	s_barrier
	s_setprio 1
	s_waitcnt lgkmcnt(0)
	v_mfma_f32_16x16x32_bf16 v[96:99], v[128:131], v[160:163], v[96:99]
	v_mfma_f32_16x16x32_bf16 v[100:103], v[136:139], v[160:163], v[100:103]
	v_mfma_f32_16x16x32_bf16 v[108:111], v[144:147], v[160:163], v[108:111]
	v_mfma_f32_16x16x32_bf16 v[104:107], v[152:155], v[160:163], v[104:107]
	v_mfma_f32_16x16x32_bf16 v[72:75], v[128:131], v[168:171], v[72:75]
	v_mfma_f32_16x16x32_bf16 v[80:83], v[136:139], v[168:171], v[80:83]
	v_mfma_f32_16x16x32_bf16 v[92:95], v[144:147], v[168:171], v[92:95]
	v_mfma_f32_16x16x32_bf16 v[88:91], v[152:155], v[168:171], v[88:91]
	v_mfma_f32_16x16x32_bf16 v[16:19], v[128:131], v[188:191], v[16:19]
	v_mfma_f32_16x16x32_bf16 v[20:23], v[136:139], v[188:191], v[20:23]
	v_mfma_f32_16x16x32_bf16 v[56:59], v[144:147], v[188:191], v[56:59]
	v_mfma_f32_16x16x32_bf16 v[40:43], v[152:155], v[188:191], v[40:43]
	v_mfma_f32_16x16x32_bf16 v[0:3], v[128:131], v[198:201], v[0:3]
	v_mfma_f32_16x16x32_bf16 v[4:7], v[136:139], v[198:201], v[4:7]
	v_mfma_f32_16x16x32_bf16 v[8:11], v[144:147], v[198:201], v[8:11]
	v_mfma_f32_16x16x32_bf16 v[12:15], v[152:155], v[198:201], v[12:15]
	s_setprio 0
	s_setprio 1
	v_mfma_f32_16x16x32_bf16 v[96:99], v[132:135], v[164:167], v[96:99]
	v_mfma_f32_16x16x32_bf16 v[100:103], v[140:143], v[164:167], v[100:103]
	v_mfma_f32_16x16x32_bf16 v[108:111], v[148:151], v[164:167], v[108:111]
	v_mfma_f32_16x16x32_bf16 v[104:107], v[156:159], v[164:167], v[104:107]
	v_mfma_f32_16x16x32_bf16 v[72:75], v[132:135], v[172:175], v[72:75]
	v_mfma_f32_16x16x32_bf16 v[80:83], v[140:143], v[172:175], v[80:83]
	v_mfma_f32_16x16x32_bf16 v[92:95], v[148:151], v[172:175], v[92:95]
	v_mfma_f32_16x16x32_bf16 v[88:91], v[156:159], v[172:175], v[88:91]
	v_mfma_f32_16x16x32_bf16 v[16:19], v[132:135], v[194:197], v[16:19]
	v_mfma_f32_16x16x32_bf16 v[20:23], v[140:143], v[194:197], v[20:23]
	v_mfma_f32_16x16x32_bf16 v[56:59], v[148:151], v[194:197], v[56:59]
	v_mfma_f32_16x16x32_bf16 v[40:43], v[156:159], v[194:197], v[40:43]
	v_mfma_f32_16x16x32_bf16 v[0:3], v[132:135], v[218:221], v[0:3]
	v_mfma_f32_16x16x32_bf16 v[4:7], v[140:143], v[218:221], v[4:7]
	v_mfma_f32_16x16x32_bf16 v[8:11], v[148:151], v[218:221], v[8:11]
	v_mfma_f32_16x16x32_bf16 v[12:15], v[156:159], v[218:221], v[12:15]
	s_setprio 0
	s_barrier
	s_add_i32 s59, s59, 2
	s_add_u32 s29, s29, 0x100
	s_addc_u32 s43, s43, 0
	s_add_u32 s6, s6, 0x100
	s_addc_u32 s7, s7, 0
	s_cmp_gt_u32 s59, 29
	s_cbranch_scc0 .LBB0_175
	s_and_b64 vcc, exec, s[12:13]
	s_cbranch_vccz .LBB0_178
	s_barrier
